# attention O epilogue: the 64 lane^1 shuffles per block are DPP quad_perm moves instead of ds_bpermute round trips
# baseline (speedup 1.0000x reference)
; __device__ __forceinline__ int crow(int r, int hi) { return (r & 3) + 8 * (r >> 2) + 4 * hi; }
; template <class TIn, class TOut, bool NB = false>
; __device__ __forceinline__ void causal_swa_block(const BlockRef<TIn, TOut>& cur, const BlockRef<TIn, TOut>& nxt, int skv, int W, char* lds, Seam<TIn>& S) {
;     ...
;     if (hi == 0) li_l[r32] = l_reg; asm volatile("s_waitcnt lgkmcnt(0)" ::: "memory");
;     float rli[16];
; #pragma unroll
;     for (int r = 0; r < 16; ++r) rli[r] = __builtin_amdgcn_rcpf(li_l[crow(r, hi)]);
;     TOut* Ow = cur.O + (size_t)(wid * QBLK) * OPITCH;
; #pragma unroll
;     for (int r = 0; r < 16; ++r) { const int orow = crow(r, hi);
; #pragma unroll
;         for (int d0 = 0; d0 < 4; ++d0) { const float v = o[d0][r] * rli[r];
;             if constexpr (same_t<TOut, float>::v) { Ow[(size_t)orow * OPITCH + d0 * 32 + r32] = v; }
;             else { const float vn = __shfl_xor(v, 1);
;                    if ((r32 & 1) == 0) *(unsigned*)(Ow + (size_t)orow * OPITCH + d0 * 32 + r32) = cvtpk(v, vn); } } }
.LBB0_843:
	s_waitcnt vmcnt(0) lgkmcnt(0)
	ds_write_b128 v210, v[104:107] offset:32768
	ds_write_b128 v210, v[108:111] offset:40960
	s_and_saveexec_b64 s[6:7], s[8:9]
	ds_write_b32 v211, v112
	s_or_b64 exec, exec, s[6:7]
	s_waitcnt lgkmcnt(0)
	ds_read_b128 v[76:79], v209
	v_and_b32_e32 v80, 64, v205
	v_add_u32_e32 v80, 64, v80
	s_ashr_i32 s31, s30, 31
	ds_read_b128 v[72:75], v209 offset:32
	ds_read_b128 v[68:71], v209 offset:64
	ds_read_b128 v[64:67], v209 offset:96
	s_waitcnt lgkmcnt(3)
	v_rcp_f32_e32 v82, v76
	v_xor_b32_e32 v76, 1, v205
	v_cmp_lt_i32_e32 vcc, v76, v80
	s_lshl_b64 s[6:7], s[30:31], 12
	v_mul_f32_e32 v32, v32, v82
	v_cndmask_b32_e32 v76, v205, v76, vcc
	v_lshlrev_b32_e32 v76, 2, v76
	s_nop 1
	v_mov_b32_dpp v83, v32 quad_perm:[1,0,3,2] row_mask:0xf bank_mask:0xf
	s_add_u32 s8, s28, s6
	s_addc_u32 s9, s29, s7
	v_and_b32_e32 v80, 1, v206
	v_lshlrev_b32_e32 v194, 1, v208
	v_cmp_eq_u32_e64 s[6:7], 0, v80
	v_lshl_add_u64 v[80:81], s[8:9], 0, v[194:195]
	v_lshlrev_b32_e32 v194, 14, v207
	v_lshl_add_u64 v[80:81], v[80:81], 0, v[194:195]
	s_and_saveexec_b64 s[8:9], s[6:7]
	s_cbranch_execz .LBB0_847
	s_waitcnt lgkmcnt(0)
	v_cvt_pk_bf16_f32 v32, v32, v83
	flat_store_dword v[80:81], v32
.LBB0_847:
	s_or_b64 exec, exec, s[8:9]
	v_mul_f32_e32 v32, v48, v82
	s_nop 1
	v_mov_b32_dpp v48, v32 quad_perm:[1,0,3,2] row_mask:0xf bank_mask:0xf
	s_and_saveexec_b64 s[8:9], s[6:7]
	s_cbranch_execz .LBB0_849
	s_waitcnt lgkmcnt(0)
	v_cvt_pk_bf16_f32 v32, v32, v48
	flat_store_dword v[80:81], v32 offset:64
.LBB0_849:
	s_or_b64 exec, exec, s[8:9]
	v_mul_f32_e32 v16, v16, v82
	s_nop 1
	v_mov_b32_dpp v32, v16 quad_perm:[1,0,3,2] row_mask:0xf bank_mask:0xf
	s_and_saveexec_b64 s[8:9], s[6:7]
	s_cbranch_execz .LBB0_851
	s_waitcnt lgkmcnt(0)
	v_cvt_pk_bf16_f32 v16, v16, v32
	flat_store_dword v[80:81], v16 offset:128
.LBB0_851:
	s_or_b64 exec, exec, s[8:9]
	v_mul_f32_e32 v0, v0, v82
	s_nop 1
	v_mov_b32_dpp v16, v0 quad_perm:[1,0,3,2] row_mask:0xf bank_mask:0xf
	s_and_saveexec_b64 s[8:9], s[6:7]
	s_cbranch_execz .LBB0_853
	s_waitcnt lgkmcnt(0)
	v_cvt_pk_bf16_f32 v0, v0, v16
	flat_store_dword v[80:81], v0 offset:192
.LBB0_853:
	s_or_b64 exec, exec, s[8:9]
	v_rcp_f32_e32 v0, v77
	s_waitcnt lgkmcnt(0)
	v_mul_f32_e32 v16, v33, v0
	s_nop 1
	v_mov_b32_dpp v32, v16 quad_perm:[1,0,3,2] row_mask:0xf bank_mask:0xf
	s_and_saveexec_b64 s[8:9], s[6:7]
	s_cbranch_execz .LBB0_855
	s_waitcnt lgkmcnt(0)
	v_cvt_pk_bf16_f32 v16, v16, v32
	v_add_co_u32_e32 v32, vcc, 0x1000, v80
	s_nop 1
	v_addc_co_u32_e32 v33, vcc, 0, v81, vcc
	flat_store_dword v[32:33], v16
.LBB0_855:
	s_or_b64 exec, exec, s[8:9]
	v_mul_f32_e32 v16, v49, v0
	s_waitcnt lgkmcnt(0)
	s_nop 1
	v_mov_b32_dpp v32, v16 quad_perm:[1,0,3,2] row_mask:0xf bank_mask:0xf
	s_and_saveexec_b64 s[8:9], s[6:7]
	s_cbranch_execz .LBB0_857
	s_waitcnt lgkmcnt(0)
	v_cvt_pk_bf16_f32 v16, v16, v32
	v_add_co_u32_e32 v32, vcc, 0x1000, v80
	s_nop 1
	v_addc_co_u32_e32 v33, vcc, 0, v81, vcc
	flat_store_dword v[32:33], v16 offset:64
.LBB0_857:
	s_or_b64 exec, exec, s[8:9]
	v_mul_f32_e32 v16, v17, v0
	s_nop 1
	v_mov_b32_dpp v17, v16 quad_perm:[1,0,3,2] row_mask:0xf bank_mask:0xf
	s_and_saveexec_b64 s[8:9], s[6:7]
	s_cbranch_execz .LBB0_859
	s_waitcnt lgkmcnt(0)
	v_cvt_pk_bf16_f32 v32, v16, v17
	v_add_co_u32_e32 v16, vcc, 0x1000, v80
	s_nop 1
	v_addc_co_u32_e32 v17, vcc, 0, v81, vcc
	flat_store_dword v[16:17], v32 offset:128
.LBB0_859:
	s_or_b64 exec, exec, s[8:9]
	v_mul_f32_e32 v0, v1, v0
	s_nop 1
	v_mov_b32_dpp v1, v0 quad_perm:[1,0,3,2] row_mask:0xf bank_mask:0xf
	s_and_saveexec_b64 s[8:9], s[6:7]
	s_cbranch_execz .LBB0_861
	s_waitcnt lgkmcnt(0)
	v_cvt_pk_bf16_f32 v16, v0, v1
	v_add_co_u32_e32 v0, vcc, 0x1000, v80
	s_nop 1
	v_addc_co_u32_e32 v1, vcc, 0, v81, vcc
	flat_store_dword v[0:1], v16 offset:192
.LBB0_861:
	s_or_b64 exec, exec, s[8:9]
	v_rcp_f32_e32 v0, v78
	s_waitcnt lgkmcnt(0)
	v_mul_f32_e32 v1, v34, v0
	s_nop 1
	v_mov_b32_dpp v16, v1 quad_perm:[1,0,3,2] row_mask:0xf bank_mask:0xf
	s_and_saveexec_b64 s[8:9], s[6:7]
	s_cbranch_execz .LBB0_863
	s_waitcnt lgkmcnt(0)
	v_cvt_pk_bf16_f32 v1, v1, v16
	v_add_co_u32_e32 v16, vcc, 0x2000, v80
	s_nop 1
	v_addc_co_u32_e32 v17, vcc, 0, v81, vcc
	flat_store_dword v[16:17], v1
.LBB0_863:
	s_or_b64 exec, exec, s[8:9]
	v_mul_f32_e32 v1, v50, v0
	s_waitcnt lgkmcnt(0)
	s_nop 1
	v_mov_b32_dpp v16, v1 quad_perm:[1,0,3,2] row_mask:0xf bank_mask:0xf
	s_and_saveexec_b64 s[8:9], s[6:7]
	s_cbranch_execz .LBB0_865
	s_waitcnt lgkmcnt(0)
	v_cvt_pk_bf16_f32 v1, v1, v16
	v_add_co_u32_e32 v16, vcc, 0x2000, v80
	s_nop 1
	v_addc_co_u32_e32 v17, vcc, 0, v81, vcc
	flat_store_dword v[16:17], v1 offset:64
.LBB0_865:
	s_or_b64 exec, exec, s[8:9]
	v_mul_f32_e32 v1, v18, v0
	s_waitcnt lgkmcnt(0)
	s_nop 1
	v_mov_b32_dpp v16, v1 quad_perm:[1,0,3,2] row_mask:0xf bank_mask:0xf
	s_and_saveexec_b64 s[8:9], s[6:7]
	s_cbranch_execz .LBB0_867
	s_waitcnt lgkmcnt(0)
	v_cvt_pk_bf16_f32 v1, v1, v16
	v_add_co_u32_e32 v16, vcc, 0x2000, v80
	s_nop 1
	v_addc_co_u32_e32 v17, vcc, 0, v81, vcc
	flat_store_dword v[16:17], v1 offset:128
.LBB0_867:
	s_or_b64 exec, exec, s[8:9]
	v_mul_f32_e32 v0, v2, v0
	s_nop 1
	v_mov_b32_dpp v1, v0 quad_perm:[1,0,3,2] row_mask:0xf bank_mask:0xf
	s_and_saveexec_b64 s[8:9], s[6:7]
	s_cbranch_execz .LBB0_869
	s_waitcnt lgkmcnt(0)
	v_cvt_pk_bf16_f32 v2, v0, v1
	v_add_co_u32_e32 v0, vcc, 0x2000, v80
	s_nop 1
	v_addc_co_u32_e32 v1, vcc, 0, v81, vcc
	flat_store_dword v[0:1], v2 offset:192
.LBB0_869:
	s_or_b64 exec, exec, s[8:9]
	v_rcp_f32_e32 v0, v79
	s_waitcnt lgkmcnt(0)
	v_mul_f32_e32 v1, v35, v0
	s_nop 1
	v_mov_b32_dpp v2, v1 quad_perm:[1,0,3,2] row_mask:0xf bank_mask:0xf
	s_and_saveexec_b64 s[8:9], s[6:7]
	s_cbranch_execz .LBB0_871
	v_add_co_u32_e32 v16, vcc, 0x3000, v80
	s_waitcnt lgkmcnt(0)
	v_cvt_pk_bf16_f32 v1, v1, v2
	s_nop 0
	v_addc_co_u32_e32 v17, vcc, 0, v81, vcc
	flat_store_dword v[16:17], v1
; __device__ __forceinline__ int crow(int r, int hi) { return (r & 3) + 8 * (r >> 2) + 4 * hi; }
; template <class TIn, class TOut, bool NB = false>
; __device__ __forceinline__ void causal_swa_block(const BlockRef<TIn, TOut>& cur, const BlockRef<TIn, TOut>& nxt, int skv, int W, char* lds, Seam<TIn>& S) {
;     ...
;     for (int r = 0; r < 16; ++r) { const int orow = crow(r, hi);
; #pragma unroll
;         for (int d0 = 0; d0 < 4; ++d0) { const float v = o[d0][r] * rli[r];
;             if constexpr (same_t<TOut, float>::v) { Ow[(size_t)orow * OPITCH + d0 * 32 + r32] = v; }
;             else { const float vn = __shfl_xor(v, 1);
;                    if ((r32 & 1) == 0) *(unsigned*)(Ow + (size_t)orow * OPITCH + d0 * 32 + r32) = cvtpk(v, vn); } } }
.LBB0_871:
	s_or_b64 exec, exec, s[8:9]
	v_mul_f32_e32 v1, v51, v0
	s_waitcnt lgkmcnt(0)
	s_nop 1
	v_mov_b32_dpp v2, v1 quad_perm:[1,0,3,2] row_mask:0xf bank_mask:0xf
	s_and_saveexec_b64 s[8:9], s[6:7]
	s_cbranch_execz .LBB0_873
	v_add_co_u32_e32 v16, vcc, 0x3000, v80
	s_waitcnt lgkmcnt(0)
	v_cvt_pk_bf16_f32 v1, v1, v2
	s_nop 0
	v_addc_co_u32_e32 v17, vcc, 0, v81, vcc
	flat_store_dword v[16:17], v1 offset:64
.LBB0_873:
	s_or_b64 exec, exec, s[8:9]
	v_mul_f32_e32 v1, v19, v0
	s_waitcnt lgkmcnt(0)
	s_nop 1
	v_mov_b32_dpp v2, v1 quad_perm:[1,0,3,2] row_mask:0xf bank_mask:0xf
	s_and_saveexec_b64 s[8:9], s[6:7]
	s_cbranch_execz .LBB0_875
	v_add_co_u32_e32 v16, vcc, 0x3000, v80
	s_waitcnt lgkmcnt(0)
	v_cvt_pk_bf16_f32 v1, v1, v2
	s_nop 0
	v_addc_co_u32_e32 v17, vcc, 0, v81, vcc
	flat_store_dword v[16:17], v1 offset:128
.LBB0_875:
	s_or_b64 exec, exec, s[8:9]
	v_mul_f32_e32 v0, v3, v0
	s_nop 1
	v_mov_b32_dpp v1, v0 quad_perm:[1,0,3,2] row_mask:0xf bank_mask:0xf
	s_and_saveexec_b64 s[8:9], s[6:7]
	s_cbranch_execz .LBB0_877
	s_waitcnt lgkmcnt(0)
	v_cvt_pk_bf16_f32 v2, v0, v1
	v_add_co_u32_e32 v0, vcc, 0x3000, v80
	s_nop 1
	v_addc_co_u32_e32 v1, vcc, 0, v81, vcc
	flat_store_dword v[0:1], v2 offset:192
.LBB0_877:
	s_or_b64 exec, exec, s[8:9]
	v_rcp_f32_e32 v0, v72
	s_waitcnt lgkmcnt(0)
	v_mul_f32_e32 v1, v36, v0
	s_nop 1
	v_mov_b32_dpp v2, v1 quad_perm:[1,0,3,2] row_mask:0xf bank_mask:0xf
	s_and_saveexec_b64 s[8:9], s[6:7]
	s_cbranch_execz .LBB0_879
	s_waitcnt lgkmcnt(0)
	v_cvt_pk_bf16_f32 v1, v1, v2
	v_add_co_u32_e32 v2, vcc, 0x8000, v80
	s_nop 1
	v_addc_co_u32_e32 v3, vcc, 0, v81, vcc
	flat_store_dword v[2:3], v1
.LBB0_879:
	s_or_b64 exec, exec, s[8:9]
	v_mul_f32_e32 v1, v52, v0
	s_waitcnt lgkmcnt(0)
	s_nop 1
	v_mov_b32_dpp v2, v1 quad_perm:[1,0,3,2] row_mask:0xf bank_mask:0xf
	s_and_saveexec_b64 s[8:9], s[6:7]
	s_cbranch_execz .LBB0_881
	s_waitcnt lgkmcnt(0)
	v_cvt_pk_bf16_f32 v1, v1, v2
	v_add_co_u32_e32 v2, vcc, 0x8000, v80
	s_nop 1
	v_addc_co_u32_e32 v3, vcc, 0, v81, vcc
	flat_store_dword v[2:3], v1 offset:64
.LBB0_881:
	s_or_b64 exec, exec, s[8:9]
	v_mul_f32_e32 v1, v20, v0
	s_waitcnt lgkmcnt(0)
	s_nop 1
	v_mov_b32_dpp v2, v1 quad_perm:[1,0,3,2] row_mask:0xf bank_mask:0xf
	s_and_saveexec_b64 s[8:9], s[6:7]
	s_cbranch_execz .LBB0_883
	s_waitcnt lgkmcnt(0)
	v_cvt_pk_bf16_f32 v1, v1, v2
	v_add_co_u32_e32 v2, vcc, 0x8000, v80
	s_nop 1
	v_addc_co_u32_e32 v3, vcc, 0, v81, vcc
	flat_store_dword v[2:3], v1 offset:128
.LBB0_883:
	s_or_b64 exec, exec, s[8:9]
	v_mul_f32_e32 v0, v4, v0
	s_nop 1
	v_mov_b32_dpp v1, v0 quad_perm:[1,0,3,2] row_mask:0xf bank_mask:0xf
	s_and_saveexec_b64 s[8:9], s[6:7]
	s_cbranch_execz .LBB0_885
	s_waitcnt lgkmcnt(0)
	v_cvt_pk_bf16_f32 v2, v0, v1
	v_add_co_u32_e32 v0, vcc, 0x8000, v80
	s_nop 1
	v_addc_co_u32_e32 v1, vcc, 0, v81, vcc
	flat_store_dword v[0:1], v2 offset:192
.LBB0_885:
	s_or_b64 exec, exec, s[8:9]
	v_rcp_f32_e32 v0, v73
	s_waitcnt lgkmcnt(0)
	v_mul_f32_e32 v1, v37, v0
	s_nop 1
	v_mov_b32_dpp v2, v1 quad_perm:[1,0,3,2] row_mask:0xf bank_mask:0xf
	s_and_saveexec_b64 s[8:9], s[6:7]
	s_cbranch_execz .LBB0_887
	s_waitcnt lgkmcnt(0)
	v_cvt_pk_bf16_f32 v1, v1, v2
	v_add_co_u32_e32 v2, vcc, 0x9000, v80
	s_nop 1
	v_addc_co_u32_e32 v3, vcc, 0, v81, vcc
	flat_store_dword v[2:3], v1
.LBB0_887:
	s_or_b64 exec, exec, s[8:9]
	v_mul_f32_e32 v1, v53, v0
	s_waitcnt lgkmcnt(0)
	s_nop 1
	v_mov_b32_dpp v2, v1 quad_perm:[1,0,3,2] row_mask:0xf bank_mask:0xf
	s_and_saveexec_b64 s[8:9], s[6:7]
	s_cbranch_execz .LBB0_889
	s_waitcnt lgkmcnt(0)
	v_cvt_pk_bf16_f32 v1, v1, v2
	v_add_co_u32_e32 v2, vcc, 0x9000, v80
	s_nop 1
	v_addc_co_u32_e32 v3, vcc, 0, v81, vcc
	flat_store_dword v[2:3], v1 offset:64
.LBB0_889:
	s_or_b64 exec, exec, s[8:9]
	v_mul_f32_e32 v1, v21, v0
	s_waitcnt lgkmcnt(0)
	s_nop 1
	v_mov_b32_dpp v2, v1 quad_perm:[1,0,3,2] row_mask:0xf bank_mask:0xf
	s_and_saveexec_b64 s[8:9], s[6:7]
	s_cbranch_execz .LBB0_891
	s_waitcnt lgkmcnt(0)
	v_cvt_pk_bf16_f32 v1, v1, v2
	v_add_co_u32_e32 v2, vcc, 0x9000, v80
	s_nop 1
	v_addc_co_u32_e32 v3, vcc, 0, v81, vcc
	flat_store_dword v[2:3], v1 offset:128
.LBB0_891:
	s_or_b64 exec, exec, s[8:9]
	v_mul_f32_e32 v0, v5, v0
	s_nop 1
	v_mov_b32_dpp v1, v0 quad_perm:[1,0,3,2] row_mask:0xf bank_mask:0xf
	s_and_saveexec_b64 s[8:9], s[6:7]
	s_cbranch_execz .LBB0_893
	s_waitcnt lgkmcnt(0)
	v_cvt_pk_bf16_f32 v2, v0, v1
	v_add_co_u32_e32 v0, vcc, 0x9000, v80
	s_nop 1
	v_addc_co_u32_e32 v1, vcc, 0, v81, vcc
	flat_store_dword v[0:1], v2 offset:192
.LBB0_893:
	s_or_b64 exec, exec, s[8:9]
	v_rcp_f32_e32 v0, v74
	s_waitcnt lgkmcnt(0)
	v_mul_f32_e32 v1, v38, v0
	s_nop 1
	v_mov_b32_dpp v2, v1 quad_perm:[1,0,3,2] row_mask:0xf bank_mask:0xf
	s_and_saveexec_b64 s[8:9], s[6:7]
	s_cbranch_execz .LBB0_895
	s_waitcnt lgkmcnt(0)
	v_cvt_pk_bf16_f32 v1, v1, v2
	v_add_co_u32_e32 v2, vcc, 0xa000, v80
	s_nop 1
	v_addc_co_u32_e32 v3, vcc, 0, v81, vcc
	flat_store_dword v[2:3], v1
.LBB0_895:
	s_or_b64 exec, exec, s[8:9]
	v_mul_f32_e32 v1, v54, v0
	s_waitcnt lgkmcnt(0)
	s_nop 1
	v_mov_b32_dpp v2, v1 quad_perm:[1,0,3,2] row_mask:0xf bank_mask:0xf
	s_and_saveexec_b64 s[8:9], s[6:7]
	s_cbranch_execz .LBB0_897
	s_waitcnt lgkmcnt(0)
	v_cvt_pk_bf16_f32 v1, v1, v2
	v_add_co_u32_e32 v2, vcc, 0xa000, v80
	s_nop 1
	v_addc_co_u32_e32 v3, vcc, 0, v81, vcc
	flat_store_dword v[2:3], v1 offset:64
.LBB0_897:
	s_or_b64 exec, exec, s[8:9]
	v_mul_f32_e32 v1, v22, v0
	s_waitcnt lgkmcnt(0)
	s_nop 1
	v_mov_b32_dpp v2, v1 quad_perm:[1,0,3,2] row_mask:0xf bank_mask:0xf
	s_and_saveexec_b64 s[8:9], s[6:7]
	s_cbranch_execz .LBB0_899
	s_waitcnt lgkmcnt(0)
	v_cvt_pk_bf16_f32 v1, v1, v2
	v_add_co_u32_e32 v2, vcc, 0xa000, v80
	s_nop 1
	v_addc_co_u32_e32 v3, vcc, 0, v81, vcc
	flat_store_dword v[2:3], v1 offset:128
; __device__ __forceinline__ int crow(int r, int hi) { return (r & 3) + 8 * (r >> 2) + 4 * hi; }
; template <class TIn, class TOut, bool NB = false>
; __device__ __forceinline__ void causal_swa_block(const BlockRef<TIn, TOut>& cur, const BlockRef<TIn, TOut>& nxt, int skv, int W, char* lds, Seam<TIn>& S) {
;     ...
;     for (int r = 0; r < 16; ++r) { const int orow = crow(r, hi);
; #pragma unroll
;         for (int d0 = 0; d0 < 4; ++d0) { const float v = o[d0][r] * rli[r];
;             if constexpr (same_t<TOut, float>::v) { Ow[(size_t)orow * OPITCH + d0 * 32 + r32] = v; }
;             else { const float vn = __shfl_xor(v, 1);
;                    if ((r32 & 1) == 0) *(unsigned*)(Ow + (size_t)orow * OPITCH + d0 * 32 + r32) = cvtpk(v, vn); } } }
.LBB0_899:
	s_or_b64 exec, exec, s[8:9]
	v_mul_f32_e32 v0, v6, v0
	s_nop 1
	v_mov_b32_dpp v1, v0 quad_perm:[1,0,3,2] row_mask:0xf bank_mask:0xf
	s_and_saveexec_b64 s[8:9], s[6:7]
	s_cbranch_execz .LBB0_901
	s_waitcnt lgkmcnt(0)
	v_cvt_pk_bf16_f32 v2, v0, v1
	v_add_co_u32_e32 v0, vcc, 0xa000, v80
	s_nop 1
	v_addc_co_u32_e32 v1, vcc, 0, v81, vcc
	flat_store_dword v[0:1], v2 offset:192
.LBB0_901:
	s_or_b64 exec, exec, s[8:9]
	v_rcp_f32_e32 v0, v75
	s_waitcnt lgkmcnt(0)
	v_mul_f32_e32 v1, v39, v0
	s_nop 1
	v_mov_b32_dpp v2, v1 quad_perm:[1,0,3,2] row_mask:0xf bank_mask:0xf
	s_and_saveexec_b64 s[8:9], s[6:7]
	s_cbranch_execz .LBB0_903
	s_waitcnt lgkmcnt(0)
	v_cvt_pk_bf16_f32 v1, v1, v2
	v_add_co_u32_e32 v2, vcc, 0xb000, v80
	s_nop 1
	v_addc_co_u32_e32 v3, vcc, 0, v81, vcc
	flat_store_dword v[2:3], v1
.LBB0_903:
	s_or_b64 exec, exec, s[8:9]
	v_mul_f32_e32 v1, v55, v0
	s_waitcnt lgkmcnt(0)
	s_nop 1
	v_mov_b32_dpp v2, v1 quad_perm:[1,0,3,2] row_mask:0xf bank_mask:0xf
	s_and_saveexec_b64 s[8:9], s[6:7]
	s_cbranch_execz .LBB0_905
	s_waitcnt lgkmcnt(0)
	v_cvt_pk_bf16_f32 v1, v1, v2
	v_add_co_u32_e32 v2, vcc, 0xb000, v80
	s_nop 1
	v_addc_co_u32_e32 v3, vcc, 0, v81, vcc
	flat_store_dword v[2:3], v1 offset:64
.LBB0_905:
	s_or_b64 exec, exec, s[8:9]
	v_mul_f32_e32 v1, v23, v0
	s_waitcnt lgkmcnt(0)
	s_nop 1
	v_mov_b32_dpp v2, v1 quad_perm:[1,0,3,2] row_mask:0xf bank_mask:0xf
	s_and_saveexec_b64 s[8:9], s[6:7]
	s_cbranch_execz .LBB0_907
	s_waitcnt lgkmcnt(0)
	v_cvt_pk_bf16_f32 v1, v1, v2
	v_add_co_u32_e32 v2, vcc, 0xb000, v80
	s_nop 1
	v_addc_co_u32_e32 v3, vcc, 0, v81, vcc
	flat_store_dword v[2:3], v1 offset:128
.LBB0_907:
	s_or_b64 exec, exec, s[8:9]
	v_mul_f32_e32 v0, v7, v0
	s_nop 1
	v_mov_b32_dpp v1, v0 quad_perm:[1,0,3,2] row_mask:0xf bank_mask:0xf
	s_and_saveexec_b64 s[8:9], s[6:7]
	s_cbranch_execz .LBB0_909
	s_waitcnt lgkmcnt(0)
	v_cvt_pk_bf16_f32 v2, v0, v1
	v_add_co_u32_e32 v0, vcc, 0xb000, v80
	s_nop 1
	v_addc_co_u32_e32 v1, vcc, 0, v81, vcc
	flat_store_dword v[0:1], v2 offset:192
.LBB0_909:
	s_or_b64 exec, exec, s[8:9]
	v_rcp_f32_e32 v0, v68
	s_waitcnt lgkmcnt(0)
	v_mul_f32_e32 v1, v40, v0
	s_nop 1
	v_mov_b32_dpp v2, v1 quad_perm:[1,0,3,2] row_mask:0xf bank_mask:0xf
	s_and_saveexec_b64 s[8:9], s[6:7]
	s_cbranch_execz .LBB0_911
	s_waitcnt lgkmcnt(0)
	v_cvt_pk_bf16_f32 v1, v1, v2
	v_add_co_u32_e32 v2, vcc, 0x10000, v80
	s_nop 1
	v_addc_co_u32_e32 v3, vcc, 0, v81, vcc
	flat_store_dword v[2:3], v1
.LBB0_911:
	s_or_b64 exec, exec, s[8:9]
	v_mul_f32_e32 v1, v56, v0
	s_waitcnt lgkmcnt(0)
	s_nop 1
	v_mov_b32_dpp v2, v1 quad_perm:[1,0,3,2] row_mask:0xf bank_mask:0xf
	s_and_saveexec_b64 s[8:9], s[6:7]
	s_cbranch_execz .LBB0_913
	s_waitcnt lgkmcnt(0)
	v_cvt_pk_bf16_f32 v1, v1, v2
	v_add_co_u32_e32 v2, vcc, 0x10000, v80
	s_nop 1
	v_addc_co_u32_e32 v3, vcc, 0, v81, vcc
	flat_store_dword v[2:3], v1 offset:64
.LBB0_913:
	s_or_b64 exec, exec, s[8:9]
	v_mul_f32_e32 v1, v24, v0
	s_waitcnt lgkmcnt(0)
	s_nop 1
	v_mov_b32_dpp v2, v1 quad_perm:[1,0,3,2] row_mask:0xf bank_mask:0xf
	s_and_saveexec_b64 s[8:9], s[6:7]
	s_cbranch_execz .LBB0_915
	s_waitcnt lgkmcnt(0)
	v_cvt_pk_bf16_f32 v1, v1, v2
	v_add_co_u32_e32 v2, vcc, 0x10000, v80
	s_nop 1
	v_addc_co_u32_e32 v3, vcc, 0, v81, vcc
	flat_store_dword v[2:3], v1 offset:128
.LBB0_915:
	s_or_b64 exec, exec, s[8:9]
	v_mul_f32_e32 v0, v8, v0
	s_nop 1
	v_mov_b32_dpp v1, v0 quad_perm:[1,0,3,2] row_mask:0xf bank_mask:0xf
	s_and_saveexec_b64 s[8:9], s[6:7]
	s_cbranch_execz .LBB0_917
	s_waitcnt lgkmcnt(0)
	v_cvt_pk_bf16_f32 v2, v0, v1
	v_add_co_u32_e32 v0, vcc, 0x10000, v80
	s_nop 1
	v_addc_co_u32_e32 v1, vcc, 0, v81, vcc
	flat_store_dword v[0:1], v2 offset:192
.LBB0_917:
	s_or_b64 exec, exec, s[8:9]
	v_rcp_f32_e32 v0, v69
	s_waitcnt lgkmcnt(0)
	v_mul_f32_e32 v1, v41, v0
	s_nop 1
	v_mov_b32_dpp v2, v1 quad_perm:[1,0,3,2] row_mask:0xf bank_mask:0xf
	s_and_saveexec_b64 s[8:9], s[6:7]
	s_cbranch_execz .LBB0_919
	s_waitcnt lgkmcnt(0)
	v_cvt_pk_bf16_f32 v1, v1, v2
	v_add_co_u32_e32 v2, vcc, 0x11000, v80
	s_nop 1
	v_addc_co_u32_e32 v3, vcc, 0, v81, vcc
	flat_store_dword v[2:3], v1
.LBB0_919:
	s_or_b64 exec, exec, s[8:9]
	v_mul_f32_e32 v1, v57, v0
	s_waitcnt lgkmcnt(0)
	s_nop 1
	v_mov_b32_dpp v2, v1 quad_perm:[1,0,3,2] row_mask:0xf bank_mask:0xf
	s_and_saveexec_b64 s[8:9], s[6:7]
	s_cbranch_execz .LBB0_921
	s_waitcnt lgkmcnt(0)
	v_cvt_pk_bf16_f32 v1, v1, v2
	v_add_co_u32_e32 v2, vcc, 0x11000, v80
	s_nop 1
	v_addc_co_u32_e32 v3, vcc, 0, v81, vcc
	flat_store_dword v[2:3], v1 offset:64
.LBB0_921:
	s_or_b64 exec, exec, s[8:9]
	v_mul_f32_e32 v1, v25, v0
	s_waitcnt lgkmcnt(0)
	s_nop 1
	v_mov_b32_dpp v2, v1 quad_perm:[1,0,3,2] row_mask:0xf bank_mask:0xf
	s_and_saveexec_b64 s[8:9], s[6:7]
	s_cbranch_execz .LBB0_923
	s_waitcnt lgkmcnt(0)
	v_cvt_pk_bf16_f32 v1, v1, v2
	v_add_co_u32_e32 v2, vcc, 0x11000, v80
	s_nop 1
	v_addc_co_u32_e32 v3, vcc, 0, v81, vcc
	flat_store_dword v[2:3], v1 offset:128
.LBB0_923:
	s_or_b64 exec, exec, s[8:9]
	v_mul_f32_e32 v0, v9, v0
	s_nop 1
	v_mov_b32_dpp v1, v0 quad_perm:[1,0,3,2] row_mask:0xf bank_mask:0xf
	s_and_saveexec_b64 s[8:9], s[6:7]
	s_cbranch_execz .LBB0_925
	s_waitcnt lgkmcnt(0)
	v_cvt_pk_bf16_f32 v2, v0, v1
	v_add_co_u32_e32 v0, vcc, 0x11000, v80
	s_nop 1
	v_addc_co_u32_e32 v1, vcc, 0, v81, vcc
	flat_store_dword v[0:1], v2 offset:192
.LBB0_925:
	s_or_b64 exec, exec, s[8:9]
	v_rcp_f32_e32 v0, v70
	s_waitcnt lgkmcnt(0)
	v_mul_f32_e32 v1, v42, v0
	s_nop 1
	v_mov_b32_dpp v2, v1 quad_perm:[1,0,3,2] row_mask:0xf bank_mask:0xf
	s_and_saveexec_b64 s[8:9], s[6:7]
	s_cbranch_execz .LBB0_927
	s_waitcnt lgkmcnt(0)
	v_cvt_pk_bf16_f32 v1, v1, v2
	v_add_co_u32_e32 v2, vcc, 0x12000, v80
	s_nop 1
	v_addc_co_u32_e32 v3, vcc, 0, v81, vcc
	flat_store_dword v[2:3], v1
; __device__ __forceinline__ int crow(int r, int hi) { return (r & 3) + 8 * (r >> 2) + 4 * hi; }
; template <class TIn, class TOut, bool NB = false>
; __device__ __forceinline__ void causal_swa_block(const BlockRef<TIn, TOut>& cur, const BlockRef<TIn, TOut>& nxt, int skv, int W, char* lds, Seam<TIn>& S) {
;     ...
;     for (int r = 0; r < 16; ++r) { const int orow = crow(r, hi);
; #pragma unroll
;         for (int d0 = 0; d0 < 4; ++d0) { const float v = o[d0][r] * rli[r];
;             if constexpr (same_t<TOut, float>::v) { Ow[(size_t)orow * OPITCH + d0 * 32 + r32] = v; }
;             else { const float vn = __shfl_xor(v, 1);
;                    if ((r32 & 1) == 0) *(unsigned*)(Ow + (size_t)orow * OPITCH + d0 * 32 + r32) = cvtpk(v, vn); } } }
.LBB0_927:
	s_or_b64 exec, exec, s[8:9]
	v_mul_f32_e32 v1, v58, v0
	s_waitcnt lgkmcnt(0)
	s_nop 1
	v_mov_b32_dpp v2, v1 quad_perm:[1,0,3,2] row_mask:0xf bank_mask:0xf
	s_and_saveexec_b64 s[8:9], s[6:7]
	s_cbranch_execz .LBB0_929
	s_waitcnt lgkmcnt(0)
	v_cvt_pk_bf16_f32 v1, v1, v2
	v_add_co_u32_e32 v2, vcc, 0x12000, v80
	s_nop 1
	v_addc_co_u32_e32 v3, vcc, 0, v81, vcc
	flat_store_dword v[2:3], v1 offset:64
.LBB0_929:
	s_or_b64 exec, exec, s[8:9]
	v_mul_f32_e32 v1, v26, v0
	s_waitcnt lgkmcnt(0)
	s_nop 1
	v_mov_b32_dpp v2, v1 quad_perm:[1,0,3,2] row_mask:0xf bank_mask:0xf
	s_and_saveexec_b64 s[8:9], s[6:7]
	s_cbranch_execz .LBB0_931
	s_waitcnt lgkmcnt(0)
	v_cvt_pk_bf16_f32 v1, v1, v2
	v_add_co_u32_e32 v2, vcc, 0x12000, v80
	s_nop 1
	v_addc_co_u32_e32 v3, vcc, 0, v81, vcc
	flat_store_dword v[2:3], v1 offset:128
.LBB0_931:
	s_or_b64 exec, exec, s[8:9]
	v_mul_f32_e32 v0, v10, v0
	s_nop 1
	v_mov_b32_dpp v1, v0 quad_perm:[1,0,3,2] row_mask:0xf bank_mask:0xf
	s_and_saveexec_b64 s[8:9], s[6:7]
	s_cbranch_execz .LBB0_933
	s_waitcnt lgkmcnt(0)
	v_cvt_pk_bf16_f32 v2, v0, v1
	v_add_co_u32_e32 v0, vcc, 0x12000, v80
	s_nop 1
	v_addc_co_u32_e32 v1, vcc, 0, v81, vcc
	flat_store_dword v[0:1], v2 offset:192
.LBB0_933:
	s_or_b64 exec, exec, s[8:9]
	v_rcp_f32_e32 v0, v71
	s_waitcnt lgkmcnt(0)
	v_mul_f32_e32 v1, v43, v0
	s_nop 1
	v_mov_b32_dpp v2, v1 quad_perm:[1,0,3,2] row_mask:0xf bank_mask:0xf
	s_and_saveexec_b64 s[8:9], s[6:7]
	s_cbranch_execz .LBB0_935
	s_waitcnt lgkmcnt(0)
	v_cvt_pk_bf16_f32 v1, v1, v2
	v_add_co_u32_e32 v2, vcc, 0x13000, v80
	s_nop 1
	v_addc_co_u32_e32 v3, vcc, 0, v81, vcc
	flat_store_dword v[2:3], v1
.LBB0_935:
	s_or_b64 exec, exec, s[8:9]
	v_mul_f32_e32 v1, v59, v0
	s_waitcnt lgkmcnt(0)
	s_nop 1
	v_mov_b32_dpp v2, v1 quad_perm:[1,0,3,2] row_mask:0xf bank_mask:0xf
	s_and_saveexec_b64 s[8:9], s[6:7]
	s_cbranch_execz .LBB0_937
	s_waitcnt lgkmcnt(0)
	v_cvt_pk_bf16_f32 v1, v1, v2
	v_add_co_u32_e32 v2, vcc, 0x13000, v80
	s_nop 1
	v_addc_co_u32_e32 v3, vcc, 0, v81, vcc
	flat_store_dword v[2:3], v1 offset:64
.LBB0_937:
	s_or_b64 exec, exec, s[8:9]
	v_mul_f32_e32 v1, v27, v0
	s_waitcnt lgkmcnt(0)
	s_nop 1
	v_mov_b32_dpp v2, v1 quad_perm:[1,0,3,2] row_mask:0xf bank_mask:0xf
	s_and_saveexec_b64 s[8:9], s[6:7]
	s_cbranch_execz .LBB0_939
	s_waitcnt lgkmcnt(0)
	v_cvt_pk_bf16_f32 v1, v1, v2
	v_add_co_u32_e32 v2, vcc, 0x13000, v80
	s_nop 1
	v_addc_co_u32_e32 v3, vcc, 0, v81, vcc
	flat_store_dword v[2:3], v1 offset:128
.LBB0_939:
	s_or_b64 exec, exec, s[8:9]
	v_mul_f32_e32 v0, v11, v0
	s_nop 1
	v_mov_b32_dpp v1, v0 quad_perm:[1,0,3,2] row_mask:0xf bank_mask:0xf
	s_and_saveexec_b64 s[8:9], s[6:7]
	s_cbranch_execz .LBB0_941
	s_waitcnt lgkmcnt(0)
	v_cvt_pk_bf16_f32 v2, v0, v1
	v_add_co_u32_e32 v0, vcc, 0x13000, v80
	s_nop 1
	v_addc_co_u32_e32 v1, vcc, 0, v81, vcc
	flat_store_dword v[0:1], v2 offset:192
.LBB0_941:
	s_or_b64 exec, exec, s[8:9]
	v_rcp_f32_e32 v0, v64
	s_waitcnt lgkmcnt(0)
	v_mul_f32_e32 v1, v44, v0
	s_nop 1
	v_mov_b32_dpp v2, v1 quad_perm:[1,0,3,2] row_mask:0xf bank_mask:0xf
	s_and_saveexec_b64 s[8:9], s[6:7]
	s_cbranch_execz .LBB0_943
	s_waitcnt lgkmcnt(0)
	v_cvt_pk_bf16_f32 v1, v1, v2
	v_add_co_u32_e32 v2, vcc, 0x18000, v80
	s_nop 1
	v_addc_co_u32_e32 v3, vcc, 0, v81, vcc
	flat_store_dword v[2:3], v1
.LBB0_943:
	s_or_b64 exec, exec, s[8:9]
	v_mul_f32_e32 v1, v60, v0
	s_waitcnt lgkmcnt(0)
	s_nop 1
	v_mov_b32_dpp v2, v1 quad_perm:[1,0,3,2] row_mask:0xf bank_mask:0xf
	s_and_saveexec_b64 s[8:9], s[6:7]
	s_cbranch_execz .LBB0_945
	s_waitcnt lgkmcnt(0)
	v_cvt_pk_bf16_f32 v1, v1, v2
	v_add_co_u32_e32 v2, vcc, 0x18000, v80
	s_nop 1
	v_addc_co_u32_e32 v3, vcc, 0, v81, vcc
	flat_store_dword v[2:3], v1 offset:64
.LBB0_945:
	s_or_b64 exec, exec, s[8:9]
	v_mul_f32_e32 v1, v28, v0
	s_waitcnt lgkmcnt(0)
	s_nop 1
	v_mov_b32_dpp v2, v1 quad_perm:[1,0,3,2] row_mask:0xf bank_mask:0xf
	s_and_saveexec_b64 s[8:9], s[6:7]
	s_cbranch_execz .LBB0_947
	s_waitcnt lgkmcnt(0)
	v_cvt_pk_bf16_f32 v1, v1, v2
	v_add_co_u32_e32 v2, vcc, 0x18000, v80
	s_nop 1
	v_addc_co_u32_e32 v3, vcc, 0, v81, vcc
	flat_store_dword v[2:3], v1 offset:128
.LBB0_947:
	s_or_b64 exec, exec, s[8:9]
	v_mul_f32_e32 v0, v12, v0
	s_nop 1
	v_mov_b32_dpp v1, v0 quad_perm:[1,0,3,2] row_mask:0xf bank_mask:0xf
	s_and_saveexec_b64 s[8:9], s[6:7]
	s_cbranch_execz .LBB0_949
	s_waitcnt lgkmcnt(0)
	v_cvt_pk_bf16_f32 v2, v0, v1
	v_add_co_u32_e32 v0, vcc, 0x18000, v80
	s_nop 1
	v_addc_co_u32_e32 v1, vcc, 0, v81, vcc
	flat_store_dword v[0:1], v2 offset:192
.LBB0_949:
	s_or_b64 exec, exec, s[8:9]
	v_rcp_f32_e32 v0, v65
	s_waitcnt lgkmcnt(0)
	v_mul_f32_e32 v1, v45, v0
	s_nop 1
	v_mov_b32_dpp v2, v1 quad_perm:[1,0,3,2] row_mask:0xf bank_mask:0xf
	s_and_saveexec_b64 s[8:9], s[6:7]
	s_cbranch_execz .LBB0_951
	s_waitcnt lgkmcnt(0)
	v_cvt_pk_bf16_f32 v1, v1, v2
	v_add_co_u32_e32 v2, vcc, 0x19000, v80
	s_nop 1
	v_addc_co_u32_e32 v3, vcc, 0, v81, vcc
	flat_store_dword v[2:3], v1
; __device__ __forceinline__ int crow(int r, int hi) { return (r & 3) + 8 * (r >> 2) + 4 * hi; }
; template <class TIn, class TOut, bool NB = false>
; __device__ __forceinline__ void causal_swa_block(const BlockRef<TIn, TOut>& cur, const BlockRef<TIn, TOut>& nxt, int skv, int W, char* lds, Seam<TIn>& S) {
;     ...
;     for (int r = 0; r < 16; ++r) { const int orow = crow(r, hi);
; #pragma unroll
;         for (int d0 = 0; d0 < 4; ++d0) { const float v = o[d0][r] * rli[r];
;             if constexpr (same_t<TOut, float>::v) { Ow[(size_t)orow * OPITCH + d0 * 32 + r32] = v; }
;             else { const float vn = __shfl_xor(v, 1);
;                    if ((r32 & 1) == 0) *(unsigned*)(Ow + (size_t)orow * OPITCH + d0 * 32 + r32) = cvtpk(v, vn); } } }
.LBB0_951:
	s_or_b64 exec, exec, s[8:9]
	v_mul_f32_e32 v1, v61, v0
	s_waitcnt lgkmcnt(0)
	s_nop 1
	v_mov_b32_dpp v2, v1 quad_perm:[1,0,3,2] row_mask:0xf bank_mask:0xf
	s_and_saveexec_b64 s[8:9], s[6:7]
	s_cbranch_execz .LBB0_953
	s_waitcnt lgkmcnt(0)
	v_cvt_pk_bf16_f32 v1, v1, v2
	v_add_co_u32_e32 v2, vcc, 0x19000, v80
	s_nop 1
	v_addc_co_u32_e32 v3, vcc, 0, v81, vcc
	flat_store_dword v[2:3], v1 offset:64
.LBB0_953:
	s_or_b64 exec, exec, s[8:9]
	v_mul_f32_e32 v1, v29, v0
	s_waitcnt lgkmcnt(0)
	s_nop 1
	v_mov_b32_dpp v2, v1 quad_perm:[1,0,3,2] row_mask:0xf bank_mask:0xf
	s_and_saveexec_b64 s[8:9], s[6:7]
	s_cbranch_execz .LBB0_955
	s_waitcnt lgkmcnt(0)
	v_cvt_pk_bf16_f32 v1, v1, v2
	v_add_co_u32_e32 v2, vcc, 0x19000, v80
	s_nop 1
	v_addc_co_u32_e32 v3, vcc, 0, v81, vcc
	flat_store_dword v[2:3], v1 offset:128
.LBB0_955:
	s_or_b64 exec, exec, s[8:9]
	v_mul_f32_e32 v0, v13, v0
	s_nop 1
	v_mov_b32_dpp v1, v0 quad_perm:[1,0,3,2] row_mask:0xf bank_mask:0xf
	s_and_saveexec_b64 s[8:9], s[6:7]
	s_cbranch_execz .LBB0_957
	s_waitcnt lgkmcnt(0)
	v_cvt_pk_bf16_f32 v2, v0, v1
	v_add_co_u32_e32 v0, vcc, 0x19000, v80
	s_nop 1
	v_addc_co_u32_e32 v1, vcc, 0, v81, vcc
	flat_store_dword v[0:1], v2 offset:192
.LBB0_957:
	s_or_b64 exec, exec, s[8:9]
	v_rcp_f32_e32 v0, v66
	s_waitcnt lgkmcnt(0)
	v_mul_f32_e32 v1, v46, v0
	s_nop 1
	v_mov_b32_dpp v2, v1 quad_perm:[1,0,3,2] row_mask:0xf bank_mask:0xf
	s_and_saveexec_b64 s[8:9], s[6:7]
	s_cbranch_execz .LBB0_959
	s_waitcnt lgkmcnt(0)
	v_cvt_pk_bf16_f32 v1, v1, v2
	v_add_co_u32_e32 v2, vcc, 0x1a000, v80
	s_nop 1
	v_addc_co_u32_e32 v3, vcc, 0, v81, vcc
	flat_store_dword v[2:3], v1
.LBB0_959:
	s_or_b64 exec, exec, s[8:9]
	v_mul_f32_e32 v1, v62, v0
	s_waitcnt lgkmcnt(0)
	s_nop 1
	v_mov_b32_dpp v2, v1 quad_perm:[1,0,3,2] row_mask:0xf bank_mask:0xf
	s_and_saveexec_b64 s[8:9], s[6:7]
	s_cbranch_execz .LBB0_961
	s_waitcnt lgkmcnt(0)
	v_cvt_pk_bf16_f32 v1, v1, v2
	v_add_co_u32_e32 v2, vcc, 0x1a000, v80
	s_nop 1
	v_addc_co_u32_e32 v3, vcc, 0, v81, vcc
	flat_store_dword v[2:3], v1 offset:64
.LBB0_961:
	s_or_b64 exec, exec, s[8:9]
	v_mul_f32_e32 v1, v30, v0
	s_waitcnt lgkmcnt(0)
	s_nop 1
	v_mov_b32_dpp v2, v1 quad_perm:[1,0,3,2] row_mask:0xf bank_mask:0xf
	s_and_saveexec_b64 s[8:9], s[6:7]
	s_cbranch_execz .LBB0_963
	s_waitcnt lgkmcnt(0)
	v_cvt_pk_bf16_f32 v1, v1, v2
	v_add_co_u32_e32 v2, vcc, 0x1a000, v80
	s_nop 1
	v_addc_co_u32_e32 v3, vcc, 0, v81, vcc
	flat_store_dword v[2:3], v1 offset:128
.LBB0_963:
	s_or_b64 exec, exec, s[8:9]
	v_mul_f32_e32 v0, v14, v0
	s_nop 1
	v_mov_b32_dpp v1, v0 quad_perm:[1,0,3,2] row_mask:0xf bank_mask:0xf
	s_and_saveexec_b64 s[8:9], s[6:7]
	s_cbranch_execz .LBB0_965
	s_waitcnt lgkmcnt(0)
	v_cvt_pk_bf16_f32 v2, v0, v1
	v_add_co_u32_e32 v0, vcc, 0x1a000, v80
	s_nop 1
	v_addc_co_u32_e32 v1, vcc, 0, v81, vcc
	flat_store_dword v[0:1], v2 offset:192
.LBB0_965:
	s_or_b64 exec, exec, s[8:9]
	v_rcp_f32_e32 v0, v67
	s_waitcnt lgkmcnt(0)
	v_mul_f32_e32 v1, v47, v0
	s_nop 1
	v_mov_b32_dpp v2, v1 quad_perm:[1,0,3,2] row_mask:0xf bank_mask:0xf
	s_and_saveexec_b64 s[8:9], s[6:7]
	s_cbranch_execz .LBB0_967
	s_waitcnt lgkmcnt(0)
	v_cvt_pk_bf16_f32 v1, v1, v2
	v_add_co_u32_e32 v2, vcc, 0x1b000, v80
	s_nop 1
	v_addc_co_u32_e32 v3, vcc, 0, v81, vcc
	flat_store_dword v[2:3], v1
.LBB0_967:
	s_or_b64 exec, exec, s[8:9]
	v_mul_f32_e32 v1, v63, v0
	s_waitcnt lgkmcnt(0)
	s_nop 1
	v_mov_b32_dpp v2, v1 quad_perm:[1,0,3,2] row_mask:0xf bank_mask:0xf
	s_and_saveexec_b64 s[8:9], s[6:7]
	s_cbranch_execz .LBB0_969
	s_waitcnt lgkmcnt(0)
	v_cvt_pk_bf16_f32 v1, v1, v2
	v_add_co_u32_e32 v2, vcc, 0x1b000, v80
	s_nop 1
	v_addc_co_u32_e32 v3, vcc, 0, v81, vcc
	flat_store_dword v[2:3], v1 offset:64
.LBB0_969:
	s_or_b64 exec, exec, s[8:9]
	v_mul_f32_e32 v1, v31, v0
	s_waitcnt lgkmcnt(0)
	s_nop 1
	v_mov_b32_dpp v2, v1 quad_perm:[1,0,3,2] row_mask:0xf bank_mask:0xf
	s_and_saveexec_b64 s[8:9], s[6:7]
	s_cbranch_execz .LBB0_971
	s_waitcnt lgkmcnt(0)
	v_cvt_pk_bf16_f32 v1, v1, v2
	v_add_co_u32_e32 v2, vcc, 0x1b000, v80
	s_nop 1
	v_addc_co_u32_e32 v3, vcc, 0, v81, vcc
	flat_store_dword v[2:3], v1 offset:128
.LBB0_971:
	s_or_b64 exec, exec, s[8:9]
	v_mul_f32_e32 v0, v15, v0
	s_nop 1
	v_mov_b32_dpp v1, v0 quad_perm:[1,0,3,2] row_mask:0xf bank_mask:0xf
	s_and_saveexec_b64 s[8:9], s[6:7]
	s_cbranch_execz .LBB0_793
	s_waitcnt lgkmcnt(0)
	v_cvt_pk_bf16_f32 v2, v0, v1
	v_add_co_u32_e32 v0, vcc, 0x1b000, v80
	s_nop 1
	v_addc_co_u32_e32 v1, vcc, 0, v81, vcc
	flat_store_dword v[0:1], v2 offset:192
	s_branch .LBB0_793
